# waves 1-7 prefetch the next MLP GEMM's bf16 weight matrix into the memory-side cache while wave 0 runs the grid barrier
# baseline (speedup 1.0000x reference)
.LBB0_21:
	s_cmp_le_i32 s59, s46
	s_cbranch_scc1 .LBB0_76
	s_waitcnt vmcnt(0)
	s_barrier
	v_readfirstlane_b32 s98, v224
	s_cmp_lt_u32 s98, 64
	s_cbranch_scc1 .Lwpf_done
	s_mov_b32 s99, 0
	s_cmp_eq_u32 s59, 6
	s_cselect_b32 s99, 0x4300000, s99
	s_cmp_eq_u32 s59, 13
	s_cselect_b32 s99, 0x6300000, s99
	s_cmp_eq_u32 s59, 7
	s_cselect_b32 s99, 0x8300000, s99
	s_cmp_eq_u32 s59, 14
	s_cselect_b32 s99, 0xa300000, s99
	s_cmp_eq_u32 s99, 0
	s_cbranch_scc1 .Lwpf_done
	s_add_u32 s98, s26, s99
	s_addc_u32 s99, s27, 0
	v_readlane_b32 vcc_lo, v251, 0
	v_subrev_u32_e32 v216, 64, v224
	s_lshl_b32 vcc_lo, vcc_lo, 17
	s_add_u32 s98, s98, vcc_lo
	s_addc_u32 s99, s99, 0
	v_add_u32_e32 v218, 0x1c0, v216
	v_add_u32_e32 v220, 0x380, v216
	v_min_u32_e32 v220, 0x3ff, v220
	v_lshlrev_b32_e32 v216, 7, v216
	v_lshlrev_b32_e32 v218, 7, v218
	v_lshlrev_b32_e32 v220, 7, v220
	global_load_dword v217, v216, s[98:99]
	global_load_dword v219, v218, s[98:99]
	global_load_dword v221, v220, s[98:99]
.Lwpf_done:
	s_and_saveexec_b64 s[0:1], s[60:61]
	s_cbranch_execz .LBB0_75
	v_readlane_b32 s2, v254, 14
	s_waitcnt vmcnt(0) expcnt(0) lgkmcnt(0)
	s_nop 0
	v_mov_b32_e32 v0, s2
	ds_read_b32 v2, v0
	v_readlane_b32 s2, v254, 15
	s_waitcnt lgkmcnt(0)
	v_cmp_ne_u32_e32 vcc, 0, v2
	v_mov_b32_e32 v0, s2
	ds_read_b32 v0, v0
	s_cbranch_vccnz .LBB0_39
	v_readlane_b32 s4, v251, 1
	v_readlane_b32 s5, v251, 2
	s_load_dwordx2 s[2:3], s[4:5], 0x4
	s_mov_b32 s31, 1
	s_waitcnt lgkmcnt(0)
	s_mul_i32 s38, s2, s19
	s_mul_i32 s38, s38, s3
	s_mov_b64 s[2:3], 0
	s_branch .LBB0_27

.LBB0_75:
	s_or_b64 exec, exec, s[0:1]
	s_waitcnt lgkmcnt(0)
	s_barrier
	s_waitcnt vmcnt(0)
